# FoX tile loop back-edge rotation: next tile's global loads issued at the loop tail in front of the barrier instead of after its release
# baseline (speedup 1.0000x reference)
; __device__ __forceinline__ void item_fox(const Params& p, int l, int bl, int h, int qb, LAS unsigned char* lds) {
;     ...
;     auto gload = [&](int kt) {
; #pragma unroll
;         for (int i = 0; i < 2; ++i) { const int c = tid + 512 * i; st[i] = *(const u32x4*)(kg + (size_t)(kt * 64 + (c >> 4)) * NP + (c & 15) * 8); }
; #pragma unroll
;         for (int i = 0; i < 2; ++i) { const int c = tid + 512 * i; st[2 + i] = *(const u32x4*)(vg + (size_t)(c >> 3) * 4096 + kt * 64 + (c & 7) * 8); }
;     };
;     ...
;     for (int kt = 0; kt < ntile; ++kt) {
;         if (kt + 1 < ntile) gload(kt + 1);
.LBB0_995:
	s_add_i32 s37, s24, 1
	s_cmp_lt_u32 s37, s25
	s_cselect_b64 s[20:21], -1, 0
	s_cmp_ge_u32 s37, s25
	s_cbranch_scc1 .LBB0_997
	s_cmp_lg_u32 s24, 0
	s_cbranch_scc1 .LBB0_997
	v_add_u32_e32 v0, s30, v181
	v_mad_i64_i32 v[2:3], s[0:1], v0, s33, v[178:179]
	v_add_u32_e32 v0, s30, v182
	v_mad_i64_i32 v[4:5], s[0:1], v0, s33, v[178:179]
	s_lshl_b64 s[0:1], s[30:31], 1
	global_load_dwordx4 v[144:147], v[2:3], off
	global_load_dwordx4 v[148:151], v[4:5], off
	v_lshl_add_u64 v[2:3], v[174:175], 0, s[0:1]
	v_lshl_add_u64 v[4:5], v[176:177], 0, s[0:1]
	global_load_dwordx4 v[152:155], v[2:3], off
	global_load_dwordx4 v[156:159], v[4:5], off

; __device__ __forceinline__ void item_fox(const Params& p, int l, int bl, int h, int qb, LAS unsigned char* lds) {
;     ...
;     auto gload = [&](int kt) {
; #pragma unroll
;         for (int i = 0; i < 2; ++i) { const int c = tid + 512 * i; st[i] = *(const u32x4*)(kg + (size_t)(kt * 64 + (c >> 4)) * NP + (c & 15) * 8); }
; #pragma unroll
;         for (int i = 0; i < 2; ++i) { const int c = tid + 512 * i; st[2 + i] = *(const u32x4*)(vg + (size_t)(c >> 3) * 4096 + kt * 64 + (c & 7) * 8); }
;     };
;     ...
;         if (kt + 1 < ntile) lstore(kt + 1);
;         __syncthreads();
;     }
.LBB0_1003:
	s_add_i32 s30, s30, 64
	s_add_i32 s27, s27, 1
	v_subrev_u32_e32 v194, 64, v194
	v_add_u32_e32 v195, 0x100, v195
	s_waitcnt lgkmcnt(0)
	s_add_i32 s0, s37, 1
	s_cmp_ge_u32 s0, s25
	s_cbranch_scc1 .Lfox_nogl
	v_add_u32_e32 v0, s30, v181
	v_mad_i64_i32 v[2:3], s[0:1], v0, s33, v[178:179]
	v_add_u32_e32 v0, s30, v182
	v_mad_i64_i32 v[4:5], s[0:1], v0, s33, v[178:179]
	s_lshl_b64 s[0:1], s[30:31], 1
	global_load_dwordx4 v[144:147], v[2:3], off
	global_load_dwordx4 v[148:151], v[4:5], off
	v_lshl_add_u64 v[2:3], v[174:175], 0, s[0:1]
	v_lshl_add_u64 v[4:5], v[176:177], 0, s[0:1]
	global_load_dwordx4 v[152:155], v[2:3], off
	global_load_dwordx4 v[156:159], v[4:5], off
.Lfox_nogl:
	s_cmp_eq_u32 s25, s37
	s_barrier
	s_cbranch_scc1 .LBB0_1010
	s_mov_b32 s24, s37
	s_branch .LBB0_995
